# dilated-attention bias LUT reads three ahead (four alternating register pairs) instead of one ahead
# baseline (speedup 1.0000x reference)
.LBB0_100:
	v_add_co_u32_e32 v8, vcc, 0x8000, v4
	s_mov_b32 s1, 0x10000
	s_nop 0
	v_addc_co_u32_e32 v9, vcc, 0, v5, vcc
	global_load_dwordx4 v[146:149], v[8:9], off
	v_add_co_u32_e32 v8, vcc, 0xa000, v4
	s_nop 1
	v_addc_co_u32_e32 v9, vcc, 0, v5, vcc
	global_load_dwordx4 v[150:153], v[8:9], off
	v_add_co_u32_e32 v8, vcc, 0xc000, v4
	s_nop 1
	v_addc_co_u32_e32 v9, vcc, 0, v5, vcc
	global_load_dwordx4 v[154:157], v[8:9], off
	v_add_co_u32_e32 v8, vcc, 0xe000, v4
	s_nop 1
	v_addc_co_u32_e32 v9, vcc, 0, v5, vcc
	global_load_dwordx4 v[158:161], v[8:9], off
	v_add_co_u32_e32 v8, vcc, s1, v4
	s_add_i32 s1, 0, 0x18000
	s_nop 0
	v_addc_co_u32_e32 v9, vcc, 0, v5, vcc
	global_load_dwordx4 v[162:165], v[8:9], off
	v_add_co_u32_e32 v8, vcc, 0x12000, v4
	s_cmp_eq_u32 s81, 0
	s_nop 0
	v_addc_co_u32_e32 v9, vcc, 0, v5, vcc
	global_load_dwordx4 v[166:169], v[8:9], off
	v_add_co_u32_e32 v8, vcc, 0x14000, v4
	s_cselect_b64 s[6:7], -1, 0
	s_nop 0
	v_addc_co_u32_e32 v9, vcc, 0, v5, vcc
	v_add_co_u32_e32 v4, vcc, 0x16000, v4
	global_load_dwordx4 v[170:173], v[8:9], off
	s_nop 0
	v_addc_co_u32_e32 v5, vcc, 0, v5, vcc
	global_load_dwordx4 v[174:177], v[4:5], off
	v_lshlrev_b32_e32 v4, 2, v6
	v_and_b32_e32 v4, 12, v4
	v_bfe_u32 v5, v6, 2, 2
	v_or_b32_e32 v8, v4, v5
	v_bitop3_b32 v4, v4, v226, v5 bitop3:0x36
	v_lshl_add_u32 v9, v227, 8, s80
	v_lshl_add_u32 v10, v4, 4, v9
	v_bitop3_b32 v232, v226, v8, 2 bitop3:0x36
	v_lshl_add_u32 v232, v232, 4, v9
	v_bitop3_b32 v236, v226, v8, 4 bitop3:0x36
	v_lshl_add_u32 v236, v236, 4, v9
	v_bitop3_b32 v237, v226, v8, 6 bitop3:0x36
	v_lshl_add_u32 v237, v237, 4, v9
	v_bitop3_b32 v238, v226, v8, 8 bitop3:0x36
	v_lshl_add_u32 v238, v238, 4, v9
	v_bitop3_b32 v239, v226, v8, 10 bitop3:0x36
	v_lshl_add_u32 v239, v239, 4, v9
	v_bitop3_b32 v240, v226, v8, 12 bitop3:0x36
	v_lshl_add_u32 v240, v240, 4, v9
	v_bitop3_b32 v100, v226, v8, 14 bitop3:0x36
	v_lshl_add_u32 v100, v100, 4, v9
	ds_read_b128 v[4:7], v10
	ds_read_b128 v[244:247], v232
	s_waitcnt vmcnt(15) lgkmcnt(1)
	v_mfma_f32_32x32x16_bf16 v[64:79], v[4:7], v[0:3], 0
	s_and_b64 s[28:29], s[12:13], s[6:7]
	s_and_b64 vcc, exec, s[28:29]
	ds_read_b128 v[4:7], v236
	s_waitcnt vmcnt(14) lgkmcnt(1)
	v_mfma_f32_32x32x16_bf16 v[64:79], v[244:247], v[202:205], v[64:79]
	ds_read_b128 v[244:247], v237
	s_waitcnt vmcnt(13) lgkmcnt(1)
	v_mfma_f32_32x32x16_bf16 v[64:79], v[4:7], v[198:201], v[64:79]
	ds_read_b128 v[4:7], v238
	s_waitcnt vmcnt(12) lgkmcnt(1)
	v_mfma_f32_32x32x16_bf16 v[64:79], v[244:247], v[194:197], v[64:79]
	ds_read_b128 v[244:247], v239
	s_waitcnt vmcnt(11) lgkmcnt(1)
	v_mfma_f32_32x32x16_bf16 v[64:79], v[4:7], v[190:193], v[64:79]
	ds_read_b128 v[4:7], v240
	s_waitcnt vmcnt(10) lgkmcnt(1)
	v_mfma_f32_32x32x16_bf16 v[64:79], v[244:247], v[186:189], v[64:79]
	ds_read_b128 v[244:247], v100
	s_waitcnt vmcnt(9) lgkmcnt(1)
	v_mfma_f32_32x32x16_bf16 v[64:79], v[4:7], v[182:185], v[64:79]
	ds_read_b128 v[4:7], v10 offset:8192
	s_waitcnt vmcnt(8) lgkmcnt(1)
	v_mfma_f32_32x32x16_bf16 v[64:79], v[244:247], v[178:181], v[64:79]
	ds_read_b128 v[244:247], v232 offset:8192
	s_waitcnt lgkmcnt(1)
	v_mfma_f32_32x32x16_bf16 v[48:63], v[4:7], v[0:3], 0
	ds_read_b128 v[4:7], v236 offset:8192
	s_waitcnt lgkmcnt(1)
	v_mfma_f32_32x32x16_bf16 v[48:63], v[244:247], v[202:205], v[48:63]
	ds_read_b128 v[244:247], v237 offset:8192
	s_waitcnt lgkmcnt(1)
	v_mfma_f32_32x32x16_bf16 v[48:63], v[4:7], v[198:201], v[48:63]
	ds_read_b128 v[4:7], v238 offset:8192
	s_waitcnt lgkmcnt(1)
	v_mfma_f32_32x32x16_bf16 v[48:63], v[244:247], v[194:197], v[48:63]
	ds_read_b128 v[244:247], v239 offset:8192
	s_waitcnt lgkmcnt(1)
	v_mfma_f32_32x32x16_bf16 v[48:63], v[4:7], v[190:193], v[48:63]
	ds_read_b128 v[4:7], v240 offset:8192
	s_waitcnt lgkmcnt(1)
	v_mfma_f32_32x32x16_bf16 v[48:63], v[244:247], v[186:189], v[48:63]
	ds_read_b128 v[244:247], v100 offset:8192
	s_waitcnt lgkmcnt(1)
	v_mfma_f32_32x32x16_bf16 v[48:63], v[4:7], v[182:185], v[48:63]
	ds_read_b128 v[4:7], v10 offset:16384
	s_waitcnt lgkmcnt(1)
	v_mfma_f32_32x32x16_bf16 v[48:63], v[244:247], v[178:181], v[48:63]
	ds_read_b128 v[244:247], v232 offset:16384
	s_waitcnt lgkmcnt(1)
	v_mfma_f32_32x32x16_bf16 v[32:47], v[4:7], v[0:3], 0
	ds_read_b128 v[4:7], v236 offset:16384
	s_waitcnt lgkmcnt(1)
	v_mfma_f32_32x32x16_bf16 v[32:47], v[244:247], v[202:205], v[32:47]
	ds_read_b128 v[244:247], v237 offset:16384
	s_waitcnt lgkmcnt(1)
	v_mfma_f32_32x32x16_bf16 v[32:47], v[4:7], v[198:201], v[32:47]
	ds_read_b128 v[4:7], v238 offset:16384
	s_waitcnt lgkmcnt(1)
	v_mfma_f32_32x32x16_bf16 v[32:47], v[244:247], v[194:197], v[32:47]
	ds_read_b128 v[244:247], v239 offset:16384
	s_waitcnt lgkmcnt(1)
	v_mfma_f32_32x32x16_bf16 v[32:47], v[4:7], v[190:193], v[32:47]
	ds_read_b128 v[4:7], v240 offset:16384
	s_waitcnt lgkmcnt(1)
	v_mfma_f32_32x32x16_bf16 v[32:47], v[244:247], v[186:189], v[32:47]
	ds_read_b128 v[244:247], v100 offset:16384
	s_waitcnt lgkmcnt(1)
	v_mfma_f32_32x32x16_bf16 v[32:47], v[4:7], v[182:185], v[32:47]
	ds_read_b128 v[4:7], v10 offset:24576
	s_waitcnt lgkmcnt(1)
	v_mfma_f32_32x32x16_bf16 v[32:47], v[244:247], v[178:181], v[32:47]
	ds_read_b128 v[244:247], v232 offset:24576
	s_waitcnt lgkmcnt(1)
	v_mfma_f32_32x32x16_bf16 v[16:31], v[4:7], v[0:3], 0
	ds_read_b128 v[4:7], v236 offset:24576
	s_waitcnt lgkmcnt(1)
	v_mfma_f32_32x32x16_bf16 v[16:31], v[244:247], v[202:205], v[16:31]
	ds_read_b128 v[244:247], v237 offset:24576
	s_waitcnt lgkmcnt(1)
	v_mfma_f32_32x32x16_bf16 v[16:31], v[4:7], v[198:201], v[16:31]
	ds_read_b128 v[4:7], v238 offset:24576
	s_waitcnt lgkmcnt(1)
	v_mfma_f32_32x32x16_bf16 v[16:31], v[244:247], v[194:197], v[16:31]
	ds_read_b128 v[244:247], v239 offset:24576
	s_waitcnt lgkmcnt(1)
	v_mfma_f32_32x32x16_bf16 v[16:31], v[4:7], v[190:193], v[16:31]
	ds_read_b128 v[4:7], v240 offset:24576
	s_waitcnt lgkmcnt(1)
	v_mfma_f32_32x32x16_bf16 v[16:31], v[244:247], v[186:189], v[16:31]
	ds_read_b128 v[244:247], v100 offset:24576
	s_waitcnt lgkmcnt(1)
	v_mfma_f32_32x32x16_bf16 v[16:31], v[4:7], v[182:185], v[16:31]
	ds_read_b128 v[4:7], v10 offset:32768
	s_waitcnt lgkmcnt(1)
	v_mfma_f32_32x32x16_bf16 v[16:31], v[244:247], v[178:181], v[16:31]
	ds_read_b128 v[244:247], v232 offset:32768
	s_waitcnt lgkmcnt(1)
	v_mfma_f32_32x32x16_bf16 v[0:15], v[4:7], v[0:3], 0
	ds_read_b128 v[232:235], v236 offset:32768
	s_waitcnt lgkmcnt(1)
	v_mfma_f32_32x32x16_bf16 v[0:15], v[244:247], v[202:205], v[0:15]
	ds_read_b128 v[244:247], v237 offset:32768
	s_waitcnt lgkmcnt(1)
	v_mfma_f32_32x32x16_bf16 v[0:15], v[232:235], v[198:201], v[0:15]
	v_mov_b32_e32 v202, 0xff800000
	ds_read_b128 v[232:235], v238 offset:32768
	s_waitcnt lgkmcnt(1)
	v_mfma_f32_32x32x16_bf16 v[0:15], v[244:247], v[194:197], v[0:15]
	ds_read_b128 v[244:247], v239 offset:32768
	s_waitcnt lgkmcnt(1)
	v_mfma_f32_32x32x16_bf16 v[0:15], v[232:235], v[190:193], v[0:15]
	v_mov_b32_e32 v195, 0xff800000
	v_mov_b32_e32 v194, 0xff800000
	v_mov_b32_e32 v197, 0xff800000
	v_mov_b32_e32 v196, 0xff800000
	ds_read_b128 v[232:235], v240 offset:32768
	s_waitcnt lgkmcnt(1)
	v_mfma_f32_32x32x16_bf16 v[0:15], v[244:247], v[186:189], v[0:15]
	v_mov_b32_e32 v190, 0xff800000
	v_mov_b32_e32 v191, 0xff800000
	v_mov_b32_e32 v193, 0xff800000
	v_mov_b32_e32 v192, 0xff800000
	ds_read_b128 v[244:247], v100 offset:32768
	s_waitcnt lgkmcnt(1)
	v_mfma_f32_32x32x16_bf16 v[0:15], v[232:235], v[182:185], v[0:15]
	v_mov_b32_e32 v100, 0xff800000
	v_mov_b32_e32 v186, 0xff800000
	v_mov_b32_e32 v189, 0xff800000
	v_mov_b32_e32 v188, 0xff800000
	s_waitcnt lgkmcnt(0)
	v_mfma_f32_32x32x16_bf16 v[0:15], v[244:247], v[178:181], v[0:15]
	v_lshlrev_b32_e32 v180, 2, v226
	v_sub_u32_e32 v181, v227, v180
	v_lshl_add_u32 v187, v181, 2, s1
	v_mov_b32_e32 v178, 0xff800000
	v_mov_b32_e32 v182, 0xff800000
	v_mov_b32_e32 v184, 0xff800000
	v_mov_b32_e32 v183, 0xff800000
	v_mov_b32_e32 v185, 0xff800000
	s_cbranch_vccnz .LBB0_102
	ds_read2_b32 v[244:245], v187 offset0:159 offset1:160
	ds_read2_b32 v[246:247], v187 offset0:157 offset1:158
	ds_read2_b32 v[232:233], v187 offset0:151 offset1:152
	v_cmp_gt_i32_e32 vcc, 2, v181
	s_mov_b32 s1, 0xff800000
	ds_read2_b32 v[234:235], v187 offset0:149 offset1:150
	s_waitcnt lgkmcnt(3)
	v_pk_add_f32 v[64:65], v[64:65], v[244:245] op_sel:[0,1] op_sel_hi:[1,0]
	s_nop 0
	v_cndmask_b32_e32 v100, v220, v65, vcc
	v_cmp_gt_i32_e32 vcc, 1, v181
	s_nop 1
	v_cndmask_b32_e32 v182, v220, v64, vcc
	v_cmp_gt_i32_e32 vcc, 4, v181
	v_max3_f32 v179, v182, s1, v100
	ds_read2_b32 v[244:245], v187 offset0:143 offset1:144
	s_waitcnt lgkmcnt(3)
	v_pk_add_f32 v[64:65], v[66:67], v[246:247] op_sel:[0,1] op_sel_hi:[1,0]
	s_nop 0
	v_cndmask_b32_e32 v183, v220, v65, vcc
	v_cmp_gt_i32_e32 vcc, 3, v181
	s_nop 1
	v_cndmask_b32_e32 v184, v220, v64, vcc
	v_cmp_gt_i32_e32 vcc, 10, v181
	v_max3_f32 v66, v179, v184, v183
	ds_read2_b32 v[246:247], v187 offset0:141 offset1:142
	s_waitcnt lgkmcnt(3)
	v_pk_add_f32 v[64:65], v[68:69], v[232:233] op_sel:[0,1] op_sel_hi:[1,0]
	s_nop 0
	v_cndmask_b32_e32 v185, v220, v65, vcc
	v_cmp_gt_i32_e32 vcc, 9, v181
	s_nop 1
	v_cndmask_b32_e32 v186, v220, v64, vcc
	v_cmp_gt_i32_e32 vcc, 12, v181
	v_max3_f32 v66, v66, v186, v185
	ds_read2_b32 v[232:233], v187 offset0:135 offset1:136
	s_waitcnt lgkmcnt(3)
	v_pk_add_f32 v[64:65], v[70:71], v[234:235] op_sel:[0,1] op_sel_hi:[1,0]
	s_nop 0
	v_cndmask_b32_e32 v188, v220, v65, vcc
	v_cmp_gt_i32_e32 vcc, 11, v181
	s_nop 1
	v_cndmask_b32_e32 v189, v220, v64, vcc
	v_cmp_gt_i32_e32 vcc, 18, v181
	v_max3_f32 v66, v66, v189, v188
	ds_read2_b32 v[234:235], v187 offset0:133 offset1:134
	s_waitcnt lgkmcnt(3)
	v_pk_add_f32 v[64:65], v[72:73], v[244:245] op_sel:[0,1] op_sel_hi:[1,0]
	s_nop 0
	v_cndmask_b32_e32 v191, v220, v65, vcc
	v_cmp_gt_i32_e32 vcc, 17, v181
	s_nop 1
	v_cndmask_b32_e32 v190, v220, v64, vcc
	v_cmp_gt_i32_e32 vcc, 20, v181
	v_max3_f32 v66, v66, v190, v191
	s_waitcnt lgkmcnt(2)
	v_pk_add_f32 v[64:65], v[74:75], v[246:247] op_sel:[0,1] op_sel_hi:[1,0]
	s_nop 0
	v_cndmask_b32_e32 v192, v220, v65, vcc
	v_cmp_gt_i32_e32 vcc, 19, v181
	s_nop 1
	v_cndmask_b32_e32 v193, v220, v64, vcc
	v_cmp_gt_i32_e32 vcc, 26, v181
	v_max3_f32 v66, v66, v193, v192
	s_waitcnt lgkmcnt(1)
	v_pk_add_f32 v[64:65], v[76:77], v[232:233] op_sel:[0,1] op_sel_hi:[1,0]
	s_nop 0
	v_cndmask_b32_e32 v194, v220, v65, vcc
	v_cmp_gt_i32_e32 vcc, 25, v181
	s_nop 1
	v_cndmask_b32_e32 v195, v220, v64, vcc
	v_cmp_gt_i32_e32 vcc, 28, v181
	v_max3_f32 v66, v66, v195, v194
	s_waitcnt lgkmcnt(0)
	v_pk_add_f32 v[64:65], v[78:79], v[234:235] op_sel:[0,1] op_sel_hi:[1,0]
	s_nop 0
	v_cndmask_b32_e32 v196, v220, v65, vcc
	v_cmp_gt_i32_e32 vcc, 27, v181
	s_nop 1
	v_cndmask_b32_e32 v197, v220, v64, vcc
	v_max3_f32 v202, v66, v197, v196
.LBB0_102:
	s_and_b64 s[28:29], s[20:21], s[6:7]
	s_and_b64 vcc, exec, s[28:29]
	s_cbranch_vccnz .LBB0_107
	ds_read2_b32 v[244:245], v187 offset0:127 offset1:128
	ds_read2_b32 v[246:247], v187 offset0:125 offset1:126
	ds_read2_b32 v[232:233], v187 offset0:119 offset1:120
	ds_read2_b32 v[234:235], v187 offset0:117 offset1:118
	s_waitcnt lgkmcnt(3)
	v_pk_add_f32 v[178:179], v[48:49], v[244:245] op_sel:[0,1] op_sel_hi:[1,0]
	v_max3_f32 v64, v202, v178, v179
	ds_read2_b32 v[244:245], v187 offset0:111 offset1:112
	s_waitcnt lgkmcnt(3)
	v_pk_add_f32 v[48:49], v[50:51], v[246:247] op_sel:[0,1] op_sel_hi:[1,0]
	v_max3_f32 v64, v64, v48, v49
	ds_read2_b32 v[246:247], v187 offset0:109 offset1:110
	s_waitcnt lgkmcnt(3)
	v_pk_add_f32 v[50:51], v[52:53], v[232:233] op_sel:[0,1] op_sel_hi:[1,0]
	v_max3_f32 v64, v64, v50, v51
	ds_read2_b32 v[232:233], v187 offset0:103 offset1:104
	s_waitcnt lgkmcnt(3)
	v_pk_add_f32 v[52:53], v[54:55], v[234:235] op_sel:[0,1] op_sel_hi:[1,0]
	v_max3_f32 v64, v64, v52, v53
	ds_read2_b32 v[234:235], v187 offset0:101 offset1:102
	s_waitcnt lgkmcnt(3)
	v_pk_add_f32 v[54:55], v[56:57], v[244:245] op_sel:[0,1] op_sel_hi:[1,0]
	v_max3_f32 v64, v64, v54, v55
	s_waitcnt lgkmcnt(2)
	v_pk_add_f32 v[56:57], v[58:59], v[246:247] op_sel:[0,1] op_sel_hi:[1,0]
	v_max3_f32 v64, v64, v56, v57
	s_waitcnt lgkmcnt(1)
	v_pk_add_f32 v[58:59], v[60:61], v[232:233] op_sel:[0,1] op_sel_hi:[1,0]
	v_max3_f32 v64, v64, v58, v59
	s_waitcnt lgkmcnt(0)
	v_pk_add_f32 v[62:63], v[62:63], v[234:235] op_sel:[0,1] op_sel_hi:[1,0]
	s_nop 0
	v_max3_f32 v202, v64, v62, v63
	s_and_b64 s[28:29], s[22:23], s[6:7]
	v_mov_b32_e32 v60, 0xff800000
	s_and_b64 vcc, exec, s[28:29]
	s_cbranch_vccz .LBB0_108

.LBB0_108:
	ds_read2_b32 v[244:245], v187 offset0:95 offset1:96
	ds_read2_b32 v[246:247], v187 offset0:93 offset1:94
	ds_read2_b32 v[232:233], v187 offset0:87 offset1:88
	ds_read2_b32 v[234:235], v187 offset0:85 offset1:86
	s_waitcnt lgkmcnt(3)
	v_pk_add_f32 v[32:33], v[32:33], v[244:245] op_sel:[0,1] op_sel_hi:[1,0]
	v_max3_f32 v61, v202, v32, v33
	ds_read2_b32 v[244:245], v187 offset0:79 offset1:80
	s_waitcnt lgkmcnt(3)
	v_pk_add_f32 v[34:35], v[34:35], v[246:247] op_sel:[0,1] op_sel_hi:[1,0]
	v_max3_f32 v61, v61, v34, v35
	ds_read2_b32 v[246:247], v187 offset0:77 offset1:78
	s_waitcnt lgkmcnt(3)
	v_pk_add_f32 v[36:37], v[36:37], v[232:233] op_sel:[0,1] op_sel_hi:[1,0]
	v_max3_f32 v61, v61, v36, v37
	ds_read2_b32 v[232:233], v187 offset0:71 offset1:72
	s_waitcnt lgkmcnt(3)
	v_pk_add_f32 v[38:39], v[38:39], v[234:235] op_sel:[0,1] op_sel_hi:[1,0]
	v_max3_f32 v61, v61, v38, v39
	ds_read2_b32 v[234:235], v187 offset0:69 offset1:70
	s_waitcnt lgkmcnt(3)
	v_pk_add_f32 v[40:41], v[40:41], v[244:245] op_sel:[0,1] op_sel_hi:[1,0]
	v_max3_f32 v61, v61, v40, v41
	s_waitcnt lgkmcnt(2)
	v_pk_add_f32 v[42:43], v[42:43], v[246:247] op_sel:[0,1] op_sel_hi:[1,0]
	v_max3_f32 v61, v61, v42, v43
	s_waitcnt lgkmcnt(1)
	v_pk_add_f32 v[44:45], v[44:45], v[232:233] op_sel:[0,1] op_sel_hi:[1,0]
	v_max3_f32 v61, v61, v44, v45
	s_waitcnt lgkmcnt(0)
	v_pk_add_f32 v[46:47], v[46:47], v[234:235] op_sel:[0,1] op_sel_hi:[1,0]
	s_nop 0
	v_max3_f32 v202, v61, v46, v47
	s_and_b64 s[28:29], s[24:25], s[6:7]
	s_and_b64 vcc, exec, s[28:29]
	s_cbranch_vccnz .LBB0_105
.LBB0_109:
	ds_read2_b32 v[244:245], v187 offset0:63 offset1:64
	ds_read2_b32 v[246:247], v187 offset0:61 offset1:62
	ds_read2_b32 v[232:233], v187 offset0:55 offset1:56
	ds_read2_b32 v[234:235], v187 offset0:53 offset1:54
	s_waitcnt lgkmcnt(3)
	v_pk_add_f32 v[60:61], v[16:17], v[244:245] op_sel:[0,1] op_sel_hi:[1,0]
	v_max3_f32 v64, v202, v60, v61
	ds_read2_b32 v[244:245], v187 offset0:47 offset1:48
	s_waitcnt lgkmcnt(3)
	v_pk_add_f32 v[16:17], v[18:19], v[246:247] op_sel:[0,1] op_sel_hi:[1,0]
	v_max3_f32 v64, v64, v16, v17
	ds_read2_b32 v[246:247], v187 offset0:45 offset1:46
	s_waitcnt lgkmcnt(3)
	v_pk_add_f32 v[18:19], v[20:21], v[232:233] op_sel:[0,1] op_sel_hi:[1,0]
	v_max3_f32 v64, v64, v18, v19
	ds_read2_b32 v[232:233], v187 offset0:39 offset1:40
	s_waitcnt lgkmcnt(3)
	v_pk_add_f32 v[20:21], v[22:23], v[234:235] op_sel:[0,1] op_sel_hi:[1,0]
	v_max3_f32 v64, v64, v20, v21
	ds_read2_b32 v[234:235], v187 offset0:37 offset1:38
	s_waitcnt lgkmcnt(3)
	v_pk_add_f32 v[22:23], v[24:25], v[244:245] op_sel:[0,1] op_sel_hi:[1,0]
	v_max3_f32 v64, v64, v22, v23
	s_waitcnt lgkmcnt(2)
	v_pk_add_f32 v[24:25], v[26:27], v[246:247] op_sel:[0,1] op_sel_hi:[1,0]
	v_max3_f32 v64, v64, v24, v25
	s_waitcnt lgkmcnt(1)
	v_pk_add_f32 v[26:27], v[28:29], v[232:233] op_sel:[0,1] op_sel_hi:[1,0]
	v_max3_f32 v64, v64, v26, v27
	s_waitcnt lgkmcnt(0)
	v_pk_add_f32 v[28:29], v[30:31], v[234:235] op_sel:[0,1] op_sel_hi:[1,0]
	s_nop 0
	v_max3_f32 v202, v64, v28, v29
	s_and_b64 s[6:7], s[40:41], s[6:7]
	v_mov_b32_e32 v70, 0xff800000
	s_and_b64 vcc, exec, s[6:7]
	s_cbranch_vccnz .LBB0_106
.LBB0_110:
	ds_read2_b32 v[244:245], v187 offset0:31 offset1:32
	ds_read2_b32 v[246:247], v187 offset0:29 offset1:30
	ds_read2_b32 v[232:233], v187 offset0:23 offset1:24
	v_cmp_lt_i32_e32 vcc, 0, v181
	ds_read2_b32 v[234:235], v187 offset0:21 offset1:22
	s_waitcnt lgkmcnt(3)
	v_pk_add_f32 v[30:31], v[0:1], v[244:245] op_sel:[0,1] op_sel_hi:[1,0]
	s_nop 0
	v_cndmask_b32_e32 v0, v220, v31, vcc
	v_cmp_lt_i32_e32 vcc, -1, v181
	s_nop 1
	v_cndmask_b32_e32 v70, v220, v30, vcc
	v_cmp_lt_i32_e32 vcc, 2, v181
	v_max3_f32 v64, v202, v70, v0
	ds_read2_b32 v[244:245], v187 offset0:15 offset1:16
	s_waitcnt lgkmcnt(3)
	v_pk_add_f32 v[2:3], v[2:3], v[246:247] op_sel:[0,1] op_sel_hi:[1,0]
	s_nop 0
	v_cndmask_b32_e32 v1, v220, v3, vcc
	v_cmp_lt_i32_e32 vcc, 1, v181
	s_nop 1
	v_cndmask_b32_e32 v71, v220, v2, vcc
	v_cmp_lt_i32_e32 vcc, 8, v181
	v_max3_f32 v30, v64, v71, v1
	ds_read2_b32 v[246:247], v187 offset0:13 offset1:14
	s_waitcnt lgkmcnt(3)
	v_pk_add_f32 v[2:3], v[4:5], v[232:233] op_sel:[0,1] op_sel_hi:[1,0]
	s_nop 0
	v_cndmask_b32_e32 v72, v220, v3, vcc
	v_cmp_lt_i32_e32 vcc, 7, v181
	s_nop 1
	v_cndmask_b32_e32 v73, v220, v2, vcc
	v_cmp_lt_i32_e32 vcc, 10, v181
	v_max3_f32 v4, v30, v73, v72
	ds_read2_b32 v[232:233], v187 offset0:7 offset1:8
	s_waitcnt lgkmcnt(3)
	v_pk_add_f32 v[2:3], v[6:7], v[234:235] op_sel:[0,1] op_sel_hi:[1,0]
	s_nop 0
	v_cndmask_b32_e32 v74, v220, v3, vcc
	v_cmp_lt_i32_e32 vcc, 9, v181
	s_nop 1
	v_cndmask_b32_e32 v75, v220, v2, vcc
	v_cmp_lt_i32_e32 vcc, 16, v181
	v_max3_f32 v4, v4, v75, v74
	ds_read2_b32 v[234:235], v187 offset0:5 offset1:6
	s_waitcnt lgkmcnt(3)
	v_pk_add_f32 v[2:3], v[8:9], v[244:245] op_sel:[0,1] op_sel_hi:[1,0]
	s_nop 0
	v_cndmask_b32_e32 v76, v220, v3, vcc
	v_cmp_lt_i32_e32 vcc, 15, v181
	s_nop 1
	v_cndmask_b32_e32 v77, v220, v2, vcc
	v_cmp_lt_i32_e32 vcc, 18, v181
	v_max3_f32 v4, v4, v77, v76
	s_waitcnt lgkmcnt(2)
	v_pk_add_f32 v[2:3], v[10:11], v[246:247] op_sel:[0,1] op_sel_hi:[1,0]
	s_nop 0
	v_cndmask_b32_e32 v78, v220, v3, vcc
	v_cmp_lt_i32_e32 vcc, 17, v181
	s_nop 1
	v_cndmask_b32_e32 v79, v220, v2, vcc
	v_cmp_lt_i32_e32 vcc, 24, v181
	v_max3_f32 v4, v4, v79, v78
	s_waitcnt lgkmcnt(1)
	v_pk_add_f32 v[2:3], v[12:13], v[232:233] op_sel:[0,1] op_sel_hi:[1,0]
	s_nop 0
	v_cndmask_b32_e32 v198, v220, v3, vcc
	v_cmp_lt_i32_e32 vcc, 23, v181
	s_nop 1
	v_cndmask_b32_e32 v199, v220, v2, vcc
	v_cmp_lt_i32_e32 vcc, 26, v181
	v_max3_f32 v4, v4, v199, v198
	s_waitcnt lgkmcnt(0)
	v_pk_add_f32 v[2:3], v[14:15], v[234:235] op_sel:[0,1] op_sel_hi:[1,0]
	s_nop 0
	v_cndmask_b32_e32 v200, v220, v3, vcc
	v_cmp_lt_i32_e32 vcc, 25, v181
	s_nop 1
	v_cndmask_b32_e32 v201, v220, v2, vcc
	v_max3_f32 v202, v4, v201, v200
